# strategy 4: one static s_setprio 1 for waves 4-7 during the attention phase (two waves per SIMD run the same program with one barrier per tile; the raise breaks their lockstep), reset to 0 after the p
# baseline (speedup 1.0000x reference)
.LBB0_1417:
	s_cmp_lt_i32 s86, 8
	s_cselect_b64 s[2:3], -1, 0
	s_and_b64 s[0:1], s[2:3], s[0:1]
	s_andn2_b64 vcc, exec, s[0:1]
	s_cbranch_vccnz .LBB0_1437
	v_mov_b32_e32 v2, v202
	s_mov_b32 s20, s74
	s_cmpk_gt_i32 s20, 0x2ff
	s_cbranch_scc1 .LBB0_1437
	v_cmp_lt_u32_e32 vcc, 0xff, v202
	s_cbranch_vccz .Lmy_attn_prio_done
	s_setprio 1
.Lmy_attn_prio_done:
	s_waitcnt vmcnt(2)
	v_add_u32_e32 v1, 0x200, v2
	s_mov_b32 s0, 0x2aaaaaab
	v_mul_hi_i32 v3, v1, s0
	v_lshrrev_b32_e32 v4, 31, v3
	v_lshrrev_b32_e32 v3, 7, v3
	v_add_u32_e32 v3, v3, v4
	s_movk_i32 s1, 0x300
	v_mul_lo_u32 v3, v3, s1
	v_sub_u32_e32 v3, v1, v3
	v_mul_hi_i32 v1, v2, s0
	s_add_u32 s4, s84, 0x2a00000
	v_lshrrev_b32_e32 v4, 31, v1
	v_ashrrev_i32_e32 v1, 1, v1
	s_addc_u32 s5, s85, 0
	v_add_u32_e32 v1, v1, v4
	v_mul_i32_i24_e32 v4, 0x2aab, v3
	s_add_u32 s8, s84, 0x4e00000
	v_lshrrev_b32_e32 v5, 31, v4
	v_ashrrev_i32_e32 v4, 17, v4
	s_addc_u32 s9, s85, 0
	v_add_u16_e32 v4, v4, v5
	s_add_u32 s10, s94, 0x1a00000
	v_bfe_i32 v161, v4, 0, 16
	v_mul_lo_u16_e32 v4, 12, v4
	s_addc_u32 s11, s95, 0
	v_sub_u16_e32 v3, v3, v4
	v_mul_lo_u32 v4, v1, 12
	v_sub_u32_e32 v8, v2, v4
	s_add_u32 s6, s84, 0xfc00000
	v_ashrrev_i32_e32 v4, 1, v2
	s_movk_i32 s0, 0xffe0
	s_addc_u32 s7, s85, 0
	v_bfi_b32 v183, s0, v4, v2
	v_mov_b32_e32 v151, 0
	v_lshlrev_b32_e32 v150, 3, v8
	v_mov_b32_e32 v4, 3
	v_lshl_add_u64 v[152:153], v[150:151], 1, s[6:7]
	v_ashrrev_i32_e32 v155, 31, v150
	v_mov_b32_e32 v154, v150
	v_lshlrev_b32_sdwa v150, v4, sext(v3) dst_sel:DWORD dst_unused:UNUSED_PAD src0_sel:DWORD src1_sel:WORD_0
	v_lshl_add_u64 v[156:157], v[150:151], 1, s[6:7]
	s_movk_i32 s6, 0xd0
	v_ashrrev_i32_e32 v182, 3, v2
	v_and_b32_e32 v7, 7, v2
	v_cmp_lt_i32_e64 s[0:1], 7, v8
	v_mov_b32_e32 v4, 0x800
	v_mov_b32_e32 v6, 0x8000
	v_cmp_gt_i32_e32 vcc, 8, v8
	v_mul_lo_u32 v184, v1, s6
	v_lshlrev_b32_e32 v185, 4, v8
	v_mad_i32_i24 v11, v161, s6, 0
	v_mov_b32_e32 v8, 4
	s_movk_i32 s6, 0x88
	v_and_b32_e32 v5, 31, v2
	v_bfe_u32 v9, v2, 5, 1
	v_cmp_lt_i16_e64 s[2:3], 7, v3
	v_cndmask_b32_e32 v4, v4, v6, vcc
	v_lshlrev_b32_e32 v6, 3, v7
	v_lshlrev_b32_sdwa v187, v8, sext(v3) dst_sel:DWORD dst_unused:UNUSED_PAD src0_sel:DWORD src1_sel:WORD_0
	v_mul_lo_u32 v3, v182, s6
	v_lshlrev_b32_e32 v7, 4, v7
	v_add3_u32 v188, 0, v3, v7
	v_mul_u32_u24_e32 v3, 0xd0, v5
	v_lshlrev_b32_e32 v7, 4, v9
	v_lshlrev_b32_e32 v2, 3, v9
	v_add3_u32 v189, 0, v3, v7
	v_mul_u32_u24_e32 v3, 0x88, v5
	v_add_u32_e32 v10, 0, v184
	v_lshlrev_b32_e32 v8, 2, v9
	s_waitcnt vmcnt(0)
	v_add3_u32 v190, 0, v2, v3
	v_mov_b64_e32 v[162:163], s[4:5]
	v_lshlrev_b32_e32 v164, 1, v2
	s_movk_i32 s14, 0xff80
	s_mov_b32 s4, 0x3f803f80
	v_mbcnt_lo_u32_b32 v2, -1, 0
	v_ashrrev_i32_e32 v159, 31, v150
	v_mov_b32_e32 v158, v150
	s_mov_b32 s13, 0
	v_mul_i32_i24_e32 v186, 0xd0, v161
	v_cndmask_b32_e64 v160, 11, 15, vcc
	s_movk_i32 s21, 0x600
	v_mov_b32_e32 v165, v151
	s_mov_b32 s15, -1
	s_mov_b32 s22, 0xd000
	v_lshlrev_b32_e32 v150, 1, v6
	v_add_u32_e32 v191, v10, v185
	v_add_u32_e32 v192, v11, v187
	v_lshlrev_b32_e32 v166, 1, v4
	s_mov_b32 s5, s4
	s_mov_b32 s6, s4
	s_mov_b32 s7, s4
	s_mov_b32 s23, 0x41000000
	v_lshlrev_b32_e32 v168, 1, v8
	v_mbcnt_hi_u32_b32 v193, -1, v2
	s_branch .LBB0_1421

.LBB0_1437:
	s_setprio 0
	s_max_i32 s75, s86, 8
	s_cmp_ge_i32 s75, s87
	s_cbranch_scc1 .LBB0_2073
	s_add_i32 s1, s86, 2
	v_writelane_b32 v254, s1, 4
	v_cmp_eq_u32_e64 s[2:3], 0, v202
	s_mul_i32 s0, s79, s78
	s_mul_i32 s0, s0, s33
	v_writelane_b32 v254, s2, 5
	s_waitcnt vmcnt(2)
	v_lshrrev_b32_e32 v1, 20, v0
	v_lshrrev_b32_e32 v0, 10, v0
	v_writelane_b32 v254, s3, 6
	v_writelane_b32 v254, s0, 7
	s_add_u32 s0, s84, 0x80200
	s_addc_u32 s1, s85, 0
	v_writelane_b32 v254, s0, 8
	v_or_b32_e32 v0, v0, v1
	s_mov_b32 s13, 0
	v_writelane_b32 v254, s1, 9
	s_add_u32 s0, s84, 0x80400
	s_addc_u32 s1, s85, 0
	v_writelane_b32 v254, s0, 10
	v_mov_b32_e32 v137, 0
	v_mov_b32_e32 v174, 0x1000
	v_writelane_b32 v254, s1, 11
	s_add_u32 s0, s84, 0x80500
	s_addc_u32 s1, s85, 0
	v_writelane_b32 v254, s0, 12
	v_mov_b32_e32 v175, 1
	v_mov_b32_e32 v176, 0x2000
	v_writelane_b32 v254, s1, 13
	s_add_u32 s0, s84, 0x80600
	s_addc_u32 s1, s85, 0
	v_writelane_b32 v254, s0, 14
	s_movk_i32 s33, 0xf000
	s_movk_i32 s80, 0xe000
	v_writelane_b32 v254, s1, 15
	s_add_u32 s0, s84, 0x80700
	s_addc_u32 s1, s85, 0
	v_writelane_b32 v254, s0, 16
	s_mov_b32 s82, 0x3a800000
	s_mov_b32 s90, 0x358637bd
	v_writelane_b32 v254, s1, 17
	s_add_u32 s0, s84, 0x80800
	s_addc_u32 s1, s85, 0
	v_writelane_b32 v254, s0, 18
	s_mov_b32 s81, 0x800000
	s_movk_i32 s83, 0x1800
	v_writelane_b32 v254, s1, 19
	s_add_u32 s0, s84, 0x80900
	s_addc_u32 s1, s85, 0
	v_writelane_b32 v254, s0, 20
	s_movk_i32 s60, 0x1fff
	s_mov_b64 s[62:63], 0x5000
	v_writelane_b32 v254, s1, 21
	s_add_u32 s0, s84, 0x80a00
	s_addc_u32 s1, s85, 0
	v_writelane_b32 v254, s0, 22
	s_movk_i32 s61, 0x60
	s_mov_b64 s[20:21], 0x80
	v_writelane_b32 v254, s1, 23
	s_add_u32 s0, s84, 0x80b00
	s_addc_u32 s1, s85, 0
	v_writelane_b32 v254, s0, 24
	s_mov_b64 s[58:59], 0x8a00800
	s_movk_i32 s56, 0x97f
	v_writelane_b32 v254, s1, 25
	s_add_u32 s0, s84, 0x80c00
	s_addc_u32 s1, s85, 0
	v_writelane_b32 v254, s0, 26
	s_movk_i32 s71, 0xc00
	s_mov_b32 s57, 0x2aaaaaab
	v_writelane_b32 v254, s1, 27
	s_add_u32 s0, s84, 0x80d00
	s_addc_u32 s1, s85, 0
	v_writelane_b32 v254, s0, 28
	s_mov_b32 s40, 0x3e16c740
	v_mov_b32_e32 v185, 0x41b17218
	v_writelane_b32 v254, s1, 29
	s_add_u32 s0, s84, 0x80e00
	s_addc_u32 s1, s85, 0
	v_writelane_b32 v254, s0, 30
	v_mov_b32_e32 v186, 0x3db504f3
	s_nop 0
	v_writelane_b32 v254, s1, 31
	s_add_u32 s0, s84, 0x80f00
	s_addc_u32 s1, s85, 0
	v_writelane_b32 v254, s0, 32
	s_nop 1
	v_writelane_b32 v254, s1, 33
	s_add_u32 s0, s84, 0x81000
	s_addc_u32 s1, s85, 0
	v_writelane_b32 v254, s0, 34
	s_nop 1
	v_writelane_b32 v254, s1, 35
	s_add_u32 s0, s84, 0x81100
	s_addc_u32 s1, s85, 0
	v_writelane_b32 v254, s0, 36
	s_nop 1
	v_writelane_b32 v254, s1, 37
	s_add_u32 s0, s84, 0x81200
	s_addc_u32 s1, s85, 0
	v_writelane_b32 v254, s0, 38
	s_nop 1
	v_writelane_b32 v254, s1, 39
	s_add_u32 s0, s84, 0x81300
	s_addc_u32 s1, s85, 0
	v_writelane_b32 v254, s0, 40
	s_nop 1
	v_writelane_b32 v254, s1, 41
	s_add_u32 s0, s84, 0x83400
	s_addc_u32 s1, s85, 0
	v_writelane_b32 v254, s0, 42
	s_nop 1
	v_writelane_b32 v254, s1, 43
	s_add_u32 s0, s84, 0x83500
	s_addc_u32 s1, s85, 0
	v_writelane_b32 v254, s0, 44
	s_add_u32 s28, s84, 0x2a00000
	s_addc_u32 s29, s85, 0
	v_writelane_b32 v254, s1, 45
	s_movk_i32 s0, 0x3ff
	v_and_or_b32 v0, v0, s0, v202
	v_cmp_eq_u32_e64 s[0:1], 0, v0
	s_lshl_b32 s68, s78, 5
	s_nop 0
	v_writelane_b32 v254, s0, 46
	s_nop 1
	v_writelane_b32 v254, s1, 47
	s_add_u32 s0, s84, 0x3a00000
	s_addc_u32 s1, s85, 0
	v_writelane_b32 v254, s0, 48
	s_nop 1
	v_writelane_b32 v254, s1, 49
	s_add_u32 s0, s84, 0x4a00000
	s_addc_u32 s1, s85, 0
	v_writelane_b32 v254, s0, 50
	s_nop 1
	v_writelane_b32 v254, s1, 51
	s_add_u32 s0, s84, 0x1c80000
	s_addc_u32 s1, s85, 0
	v_writelane_b32 v254, s0, 52
	s_nop 1
	v_writelane_b32 v254, s1, 53
	s_add_u32 s0, s84, 0xd000000
	s_addc_u32 s1, s85, 0
	v_writelane_b32 v254, s0, 54
	s_nop 1
	v_writelane_b32 v254, s1, 55
	s_add_u32 s0, s84, 0x1480000
	s_addc_u32 s1, s85, 0
	v_writelane_b32 v254, s0, 56
	s_nop 1
	v_writelane_b32 v254, s1, 57
	s_add_u32 s0, s84, 0x6a00000
	s_addc_u32 s1, s85, 0
	v_writelane_b32 v254, s0, 58
	s_nop 1
	v_writelane_b32 v254, s1, 59
	s_add_u32 s0, s84, 0x2080000
	s_addc_u32 s1, s85, 0
	v_writelane_b32 v254, s0, 60
	s_nop 1
	v_writelane_b32 v254, s1, 61
	s_add_u32 s0, s84, 0xf000000
	s_addc_u32 s1, s85, 0
	v_writelane_b32 v254, s0, 62
	s_nop 1
	v_writelane_b32 v254, s1, 63
	s_add_u32 s0, s84, 0x2480000
	s_addc_u32 s1, s85, 0
	s_add_u32 s96, s84, 0x8a00000
	v_writelane_b32 v255, s0, 0
	s_addc_u32 s97, s85, 0
	s_nop 0
	v_writelane_b32 v255, s1, 1
	s_add_u32 s0, s94, 0x1a00000
	s_addc_u32 s1, s95, 0
	v_writelane_b32 v255, s0, 2
	s_nop 1
	v_writelane_b32 v255, s1, 3
	s_add_u32 s0, s84, 0x2680000
	s_addc_u32 s1, s85, 0
	v_writelane_b32 v255, s0, 4
	s_nop 1
	v_writelane_b32 v255, s1, 5
	s_add_u32 s0, s84, 0x7200000
	s_addc_u32 s1, s85, 0
	v_writelane_b32 v255, s0, 6
	s_nop 1
	v_writelane_b32 v255, s1, 7
	s_add_u32 s0, s84, 0x2780000
	s_addc_u32 s1, s85, 0
	v_writelane_b32 v255, s0, 8
	s_nop 1
	v_writelane_b32 v255, s1, 9
	s_add_u32 s0, s84, 0x2950000
	s_addc_u32 s1, s85, 0
	v_writelane_b32 v255, s0, 10
	s_nop 1
	v_writelane_b32 v255, s1, 11
	s_add_u32 s0, s94, 0x3c00000
	s_addc_u32 s1, s95, 0
	v_writelane_b32 v255, s0, 12
	s_nop 1
	v_writelane_b32 v255, s1, 13
	s_add_u32 s0, s84, 0x2910000
	s_addc_u32 s1, s85, 0
	v_writelane_b32 v255, s0, 14
	s_nop 1
	v_writelane_b32 v255, s1, 15
	s_add_u32 s0, s84, 0x4e00000
	s_addc_u32 s1, s85, 0
	v_writelane_b32 v255, s0, 16
	s_nop 1
	v_writelane_b32 v255, s1, 17
	s_add_u32 s0, s84, 0xea00000
	s_addc_u32 s1, s85, 0
	v_writelane_b32 v255, s0, 18
	s_nop 1
	v_writelane_b32 v255, s1, 19
	s_add_u32 s0, s84, 0x2880000
	s_addc_u32 s1, s85, 0
	v_writelane_b32 v255, s0, 20
	s_nop 1
	v_writelane_b32 v255, s1, 21
	s_add_u32 s0, s84, 0xb00000
	s_addc_u32 s1, s85, 0
	s_ashr_i32 s41, s78, 31
	s_add_u32 s14, s84, 0x20000
	v_writelane_b32 v255, s0, 22
	s_addc_u32 s15, s85, 0
	s_nop 0
	v_writelane_b32 v255, s1, 23
	s_add_u32 s0, s84, 0x600000
	s_addc_u32 s1, s85, 0
	s_abs_i32 s79, s78
	v_cvt_f32_u32_e32 v0, s79
	v_writelane_b32 v255, s0, 24
	v_rcp_iflag_f32_e32 v0, v0
	s_nop 0
	v_writelane_b32 v255, s1, 25
	s_sub_i32 s0, 0, s79
	v_mul_f32_e32 v0, 0x4f7ffffe, v0
	v_cvt_u32_f32_e32 v0, v0
	s_nop 0
	v_readfirstlane_b32 s1, v0
	s_mul_i32 s0, s0, s1
	s_mul_hi_u32 s0, s1, s0
	s_add_i32 s70, s1, s0
	s_add_u32 s0, s94, 0x3c00
	s_addc_u32 s1, s95, 0
	s_ashr_i32 s69, s68, 31
	v_writelane_b32 v255, s0, 26
	s_lshl_b64 s[72:73], s[68:69], 12
	v_mbcnt_lo_u32_b32 v0, -1, 0
	v_writelane_b32 v255, s1, 27
	s_add_u32 s0, s84, 0x2a01e00
	s_addc_u32 s1, s85, 0
	v_writelane_b32 v255, s0, 28
	s_lshl_b64 s[76:77], s[68:69], 11
	v_mbcnt_hi_u32_b32 v177, -1, v0
	v_writelane_b32 v255, s1, 29
	s_add_u32 s0, s84, 0x3a01e00
	s_addc_u32 s1, s85, 0
	v_writelane_b32 v255, s0, 30
	v_and_b32_e32 v0, 64, v177
	v_add_u32_e32 v178, 64, v0
	v_writelane_b32 v255, s1, 31
	s_add_u32 s0, s94, 0xc00
	s_addc_u32 s1, s95, 0
	v_writelane_b32 v255, s0, 32
	v_xor_b32_e32 v179, 1, v177
	v_xor_b32_e32 v180, 2, v177
	v_writelane_b32 v255, s1, 33
	s_add_u32 s0, s84, 0xd001e00
	s_addc_u32 s1, s85, 0
	v_writelane_b32 v255, s0, 34
	v_xor_b32_e32 v181, 4, v177
	v_xor_b32_e32 v182, 8, v177
	v_writelane_b32 v255, s1, 35
	s_add_i32 s0, 0, 0x23fc0
	v_writelane_b32 v255, s0, 36
	s_add_i32 s0, 0, 0x23fc4
	v_writelane_b32 v255, s0, 37
	v_writelane_b32 v255, s79, 38
	v_writelane_b32 v255, s68, 39
	v_xor_b32_e32 v183, 16, v177
	v_xor_b32_e32 v184, 32, v177
	v_writelane_b32 v255, s69, 40
	v_writelane_b32 v255, s70, 41
	v_writelane_b32 v255, s72, 42
	s_nop 1
	v_writelane_b32 v255, s73, 43
	v_writelane_b32 v255, s76, 44
	s_nop 1
	v_writelane_b32 v255, s77, 45
	s_branch .LBB0_1440
